# stacked: v35 + rotated attention back edge + hoisted V^T LDS reads + trimmed deferred-block pads
# baseline (speedup 1.0000x reference)
.LBB0_885:
	s_cmp_eq_u32 s92, 0
	s_cselect_b64 s[4:5], -1, 0
	s_or_b64 s[4:5], s[86:87], s[4:5]
	s_sub_i32 s6, s92, 64
	s_cmp_gt_i32 s6, s64
	s_cselect_b64 s[6:7], -1, 0
	s_or_b64 s[4:5], s[4:5], s[6:7]
	s_and_b64 vcc, exec, s[4:5]
	s_cbranch_vccnz .LBB0_893
	s_mulk_i32 s0, 0x4800
	v_add_u32_e32 v17, s0, v244
	ds_read_b128 v[4:7], v17 offset:51200
	ds_read_b128 v[8:11], v17 offset:55808
	ds_read_b128 v[12:15], v17 offset:60416
	ds_read_b128 v[176:179], v17 offset:65024
	v_max3_f32 v2, v98, v99, v100
	v_max3_f32 v16, v101, v102, v103
	v_max3_f32 v174, v104, v105, v106
	v_max3_f32 v175, v107, v108, v109
	v_max3_f32 v2, v2, v110, v111
	v_max3_f32 v16, v16, v112, v113
	v_max3_f32 v174, v174, v82, v83
	v_max3_f32 v175, v175, v84, v85
	v_max3_f32 v2, v2, v86, v87
	v_max3_f32 v16, v16, v88, v89
	v_max3_f32 v174, v174, v90, v91
	v_max3_f32 v175, v175, v92, v93
	v_max3_f32 v2, v2, v94, v95
	v_max3_f32 v16, v16, v96, v97
	v_max3_f32 v2, v2, v16, v174
	v_max_f32_e32 v2, v2, v175
	v_mov_b32_e32 v16, v2
	s_nop 1
	v_permlane32_swap_b32_e32 v2, v16
	v_max_f32_e32 v2, v2, v16
	v_sub_f32_e32 v16, v2, v252
	v_mul_f32_e32 v16, 0x3dd53b94, v16
	s_mov_b32 s0, 0x41380000
	v_cmp_ge_f32_e32 vcc, s0, v16
	s_cmp_eq_u64 vcc, exec
	s_cbranch_scc1 .Ld2_exp
	v_max_f32_e32 v2, v2, v2
	v_max_f32_e32 v16, v252, v252
	v_max_f32_e32 v16, v16, v2
	v_sub_f32_e32 v2, v252, v16
	v_mul_f32_e32 v2, 0x3dd53b94, v2
	v_exp_f32_e32 v2, v2
	v_mov_b32_e32 v252, v16
	v_pk_mul_f32 v[80:81], v[80:81], v[2:3] op_sel_hi:[1,0]
	v_pk_mul_f32 v[78:79], v[78:79], v[2:3] op_sel_hi:[1,0]
	v_pk_mul_f32 v[76:77], v[76:77], v[2:3] op_sel_hi:[1,0]
	v_pk_mul_f32 v[74:75], v[74:75], v[2:3] op_sel_hi:[1,0]
	v_pk_mul_f32 v[72:73], v[72:73], v[2:3] op_sel_hi:[1,0]
	v_pk_mul_f32 v[70:71], v[70:71], v[2:3] op_sel_hi:[1,0]
	v_pk_mul_f32 v[68:69], v[68:69], v[2:3] op_sel_hi:[1,0]
	v_pk_mul_f32 v[66:67], v[66:67], v[2:3] op_sel_hi:[1,0]
	v_pk_mul_f32 v[64:65], v[64:65], v[2:3] op_sel_hi:[1,0]
	v_pk_mul_f32 v[62:63], v[62:63], v[2:3] op_sel_hi:[1,0]
	v_pk_mul_f32 v[60:61], v[60:61], v[2:3] op_sel_hi:[1,0]
	v_pk_mul_f32 v[58:59], v[58:59], v[2:3] op_sel_hi:[1,0]
	v_pk_mul_f32 v[56:57], v[56:57], v[2:3] op_sel_hi:[1,0]
	v_pk_mul_f32 v[54:55], v[54:55], v[2:3] op_sel_hi:[1,0]
	v_pk_mul_f32 v[52:53], v[52:53], v[2:3] op_sel_hi:[1,0]
	v_pk_mul_f32 v[50:51], v[50:51], v[2:3] op_sel_hi:[1,0]
	v_pk_mul_f32 v[48:49], v[48:49], v[2:3] op_sel_hi:[1,0]
	v_pk_mul_f32 v[46:47], v[46:47], v[2:3] op_sel_hi:[1,0]
	v_pk_mul_f32 v[44:45], v[44:45], v[2:3] op_sel_hi:[1,0]
	v_pk_mul_f32 v[42:43], v[42:43], v[2:3] op_sel_hi:[1,0]
	v_pk_mul_f32 v[40:41], v[40:41], v[2:3] op_sel_hi:[1,0]
	v_pk_mul_f32 v[38:39], v[38:39], v[2:3] op_sel_hi:[1,0]
	v_pk_mul_f32 v[36:37], v[36:37], v[2:3] op_sel_hi:[1,0]
	v_pk_mul_f32 v[34:35], v[34:35], v[2:3] op_sel_hi:[1,0]
	v_pk_mul_f32 v[32:33], v[32:33], v[2:3] op_sel_hi:[1,0]
	v_pk_mul_f32 v[30:31], v[30:31], v[2:3] op_sel_hi:[1,0]
	v_pk_mul_f32 v[28:29], v[28:29], v[2:3] op_sel_hi:[1,0]
	v_pk_mul_f32 v[26:27], v[26:27], v[2:3] op_sel_hi:[1,0]
	v_pk_mul_f32 v[24:25], v[24:25], v[2:3] op_sel_hi:[1,0]
	v_pk_mul_f32 v[22:23], v[22:23], v[2:3] op_sel_hi:[1,0]
	v_pk_mul_f32 v[20:21], v[20:21], v[2:3] op_sel_hi:[1,0]
	v_pk_mul_f32 v[18:19], v[18:19], v[2:3] op_sel_hi:[1,0]
	v_mul_f32_e32 v250, v250, v2

.LBB0_899:
	s_and_b64 vcc, exec, s[88:89]
	s_cbranch_vccz .LBB0_881
	s_lshl_b32 s0, s33, 6
	s_sub_i32 s0, s0, 64
	s_cmp_gt_i32 s0, s64
	s_cbranch_scc1 .LBB0_881
	s_mul_i32 s0, s71, 0x4800
	v_add_u32_e32 v17, s0, v244
	ds_read_b128 v[4:7], v17 offset:51200
	ds_read_b128 v[8:11], v17 offset:55808
	ds_read_b128 v[12:15], v17 offset:60416
	ds_read_b128 v[176:179], v17 offset:65024
	v_max3_f32 v2, v98, v99, v100
	v_max3_f32 v16, v101, v102, v103
	v_max3_f32 v174, v104, v105, v106
	v_max3_f32 v175, v107, v108, v109
	v_max3_f32 v2, v2, v110, v111
	v_max3_f32 v16, v16, v112, v113
	v_max3_f32 v174, v174, v82, v83
	v_max3_f32 v175, v175, v84, v85
	v_max3_f32 v2, v2, v86, v87
	v_max3_f32 v16, v16, v88, v89
	v_max3_f32 v174, v174, v90, v91
	v_max3_f32 v175, v175, v92, v93
	v_max3_f32 v2, v2, v94, v95
	v_max3_f32 v16, v16, v96, v97
	v_max3_f32 v2, v2, v16, v174
	v_max_f32_e32 v2, v2, v175
	v_mov_b32_e32 v16, v2
	s_nop 1
	v_permlane32_swap_b32_e32 v2, v16
	v_max_f32_e32 v2, v2, v16
	v_sub_f32_e32 v16, v2, v252
	v_mul_f32_e32 v16, 0x3dd53b94, v16
	s_mov_b32 s0, 0x41380000
	v_cmp_ge_f32_e32 vcc, s0, v16
	s_cmp_eq_u64 vcc, exec
	s_cbranch_scc1 .Ld3_exp
	v_max_f32_e32 v2, v2, v2
	v_max_f32_e32 v16, v252, v252
	v_max_f32_e32 v16, v16, v2
	v_sub_f32_e32 v2, v252, v16
	v_mul_f32_e32 v2, 0x3dd53b94, v2
	v_exp_f32_e32 v2, v2
	v_mov_b32_e32 v252, v16
	v_pk_mul_f32 v[80:81], v[80:81], v[2:3] op_sel_hi:[1,0]
	v_pk_mul_f32 v[78:79], v[78:79], v[2:3] op_sel_hi:[1,0]
	v_pk_mul_f32 v[76:77], v[76:77], v[2:3] op_sel_hi:[1,0]
	v_pk_mul_f32 v[74:75], v[74:75], v[2:3] op_sel_hi:[1,0]
	v_pk_mul_f32 v[72:73], v[72:73], v[2:3] op_sel_hi:[1,0]
	v_pk_mul_f32 v[70:71], v[70:71], v[2:3] op_sel_hi:[1,0]
	v_pk_mul_f32 v[68:69], v[68:69], v[2:3] op_sel_hi:[1,0]
	v_pk_mul_f32 v[66:67], v[66:67], v[2:3] op_sel_hi:[1,0]
	v_pk_mul_f32 v[64:65], v[64:65], v[2:3] op_sel_hi:[1,0]
	v_pk_mul_f32 v[62:63], v[62:63], v[2:3] op_sel_hi:[1,0]
	v_pk_mul_f32 v[60:61], v[60:61], v[2:3] op_sel_hi:[1,0]
	v_pk_mul_f32 v[58:59], v[58:59], v[2:3] op_sel_hi:[1,0]
	v_pk_mul_f32 v[56:57], v[56:57], v[2:3] op_sel_hi:[1,0]
	v_pk_mul_f32 v[54:55], v[54:55], v[2:3] op_sel_hi:[1,0]
	v_pk_mul_f32 v[52:53], v[52:53], v[2:3] op_sel_hi:[1,0]
	v_pk_mul_f32 v[50:51], v[50:51], v[2:3] op_sel_hi:[1,0]
	v_pk_mul_f32 v[48:49], v[48:49], v[2:3] op_sel_hi:[1,0]
	v_pk_mul_f32 v[46:47], v[46:47], v[2:3] op_sel_hi:[1,0]
	v_pk_mul_f32 v[44:45], v[44:45], v[2:3] op_sel_hi:[1,0]
	v_pk_mul_f32 v[42:43], v[42:43], v[2:3] op_sel_hi:[1,0]
	v_pk_mul_f32 v[40:41], v[40:41], v[2:3] op_sel_hi:[1,0]
	v_pk_mul_f32 v[38:39], v[38:39], v[2:3] op_sel_hi:[1,0]
	v_pk_mul_f32 v[36:37], v[36:37], v[2:3] op_sel_hi:[1,0]
	v_pk_mul_f32 v[34:35], v[34:35], v[2:3] op_sel_hi:[1,0]
	v_pk_mul_f32 v[32:33], v[32:33], v[2:3] op_sel_hi:[1,0]
	v_pk_mul_f32 v[30:31], v[30:31], v[2:3] op_sel_hi:[1,0]
	v_pk_mul_f32 v[28:29], v[28:29], v[2:3] op_sel_hi:[1,0]
	v_pk_mul_f32 v[26:27], v[26:27], v[2:3] op_sel_hi:[1,0]
	v_pk_mul_f32 v[24:25], v[24:25], v[2:3] op_sel_hi:[1,0]
	v_pk_mul_f32 v[22:23], v[22:23], v[2:3] op_sel_hi:[1,0]
	v_pk_mul_f32 v[20:21], v[20:21], v[2:3] op_sel_hi:[1,0]
	v_pk_mul_f32 v[18:19], v[18:19], v[2:3] op_sel_hi:[1,0]
	v_mul_f32_e32 v250, v250, v2
